# ret_prompt chunk loop: K'^T staging rounds bf16 pairs with one v_cvt_pk_bf16_f32 (same RNE) instead of per-element bfe+add3; the four LDS->MFMA loops fully unrolled with operand reads issued ahead int
# speedup vs baseline: 1.0417x; 1.0082x over previous
.Lret_pf_skip:
.LBB0_696:
	v_add_u32_e32 v139, 0x10800, v181
	ds_read_b128 v[200:203], v180
	ds_read_b128 v[210:213], v180 offset:8448
	ds_read_b128 v[204:207], v139
	ds_read_b128 v[232:235], v139 offset:8448
	ds_read_b128 v[236:239], v139 offset:16896
	ds_read_b128 v[240:243], v139 offset:25344
	ds_read_b128 v[224:227], v180 offset:64
	ds_read_b128 v[228:231], v180 offset:8512
	s_waitcnt lgkmcnt(5)
	v_mfma_f32_16x16x32_bf16 v[118:121], v[204:207], v[200:203], v[118:121]
	v_mfma_f32_16x16x32_bf16 v[114:117], v[204:207], v[210:213], v[114:117]
	ds_read_b128 v[204:207], v139 offset:64
	s_waitcnt lgkmcnt(5)
	v_mfma_f32_16x16x32_bf16 v[110:113], v[232:235], v[200:203], v[110:113]
	v_mfma_f32_16x16x32_bf16 v[106:109], v[232:235], v[210:213], v[106:109]
	ds_read_b128 v[232:235], v139 offset:8512
	s_waitcnt lgkmcnt(5)
	v_mfma_f32_16x16x32_bf16 v[102:105], v[236:239], v[200:203], v[102:105]
	v_mfma_f32_16x16x32_bf16 v[98:101], v[236:239], v[210:213], v[98:101]
	ds_read_b128 v[236:239], v139 offset:16960
	s_waitcnt lgkmcnt(5)
	v_mfma_f32_16x16x32_bf16 v[94:97], v[240:243], v[200:203], v[94:97]
	v_mfma_f32_16x16x32_bf16 v[88:91], v[240:243], v[210:213], v[90:93]
	ds_read_b128 v[240:243], v139 offset:25408
	ds_read_b128 v[200:203], v180 offset:128
	ds_read_b128 v[210:213], v180 offset:8576
	s_waitcnt lgkmcnt(5)
	v_mfma_f32_16x16x32_bf16 v[118:121], v[204:207], v[224:227], v[118:121]
	v_mfma_f32_16x16x32_bf16 v[114:117], v[204:207], v[228:231], v[114:117]
	ds_read_b128 v[204:207], v139 offset:128
	s_waitcnt lgkmcnt(5)
	v_mfma_f32_16x16x32_bf16 v[110:113], v[232:235], v[224:227], v[110:113]
	v_mfma_f32_16x16x32_bf16 v[106:109], v[232:235], v[228:231], v[106:109]
	ds_read_b128 v[232:235], v139 offset:8576
	s_waitcnt lgkmcnt(5)
	v_mfma_f32_16x16x32_bf16 v[102:105], v[236:239], v[224:227], v[102:105]
	v_mfma_f32_16x16x32_bf16 v[98:101], v[236:239], v[228:231], v[98:101]
	ds_read_b128 v[236:239], v139 offset:17024
	s_waitcnt lgkmcnt(5)
	v_mfma_f32_16x16x32_bf16 v[94:97], v[240:243], v[224:227], v[94:97]
	v_mfma_f32_16x16x32_bf16 v[90:93], v[240:243], v[228:231], v[88:91]
	ds_read_b128 v[240:243], v139 offset:25472
	ds_read_b128 v[224:227], v180 offset:192
	ds_read_b128 v[228:231], v180 offset:8640
	s_waitcnt lgkmcnt(5)
	v_mfma_f32_16x16x32_bf16 v[118:121], v[204:207], v[200:203], v[118:121]
	v_mfma_f32_16x16x32_bf16 v[114:117], v[204:207], v[210:213], v[114:117]
	ds_read_b128 v[204:207], v139 offset:192
	s_waitcnt lgkmcnt(5)
	v_mfma_f32_16x16x32_bf16 v[110:113], v[232:235], v[200:203], v[110:113]
	v_mfma_f32_16x16x32_bf16 v[106:109], v[232:235], v[210:213], v[106:109]
	ds_read_b128 v[232:235], v139 offset:8640
	s_waitcnt lgkmcnt(5)
	v_mfma_f32_16x16x32_bf16 v[102:105], v[236:239], v[200:203], v[102:105]
	v_mfma_f32_16x16x32_bf16 v[98:101], v[236:239], v[210:213], v[98:101]
	ds_read_b128 v[236:239], v139 offset:17088
	s_waitcnt lgkmcnt(5)
	v_mfma_f32_16x16x32_bf16 v[94:97], v[240:243], v[200:203], v[94:97]
	v_mfma_f32_16x16x32_bf16 v[88:91], v[240:243], v[210:213], v[90:93]
	ds_read_b128 v[240:243], v139 offset:25536
	ds_read_b128 v[200:203], v180 offset:256
	ds_read_b128 v[210:213], v180 offset:8704
	s_waitcnt lgkmcnt(5)
	v_mfma_f32_16x16x32_bf16 v[118:121], v[204:207], v[224:227], v[118:121]
	v_mfma_f32_16x16x32_bf16 v[114:117], v[204:207], v[228:231], v[114:117]
	ds_read_b128 v[204:207], v139 offset:256
	s_waitcnt lgkmcnt(5)
	v_mfma_f32_16x16x32_bf16 v[110:113], v[232:235], v[224:227], v[110:113]
	v_mfma_f32_16x16x32_bf16 v[106:109], v[232:235], v[228:231], v[106:109]
	ds_read_b128 v[232:235], v139 offset:8704
	s_waitcnt lgkmcnt(5)
	v_mfma_f32_16x16x32_bf16 v[102:105], v[236:239], v[224:227], v[102:105]
	v_mfma_f32_16x16x32_bf16 v[98:101], v[236:239], v[228:231], v[98:101]
	ds_read_b128 v[236:239], v139 offset:17152
	s_waitcnt lgkmcnt(5)
	v_mfma_f32_16x16x32_bf16 v[94:97], v[240:243], v[224:227], v[94:97]
	v_mfma_f32_16x16x32_bf16 v[90:93], v[240:243], v[228:231], v[88:91]
	ds_read_b128 v[240:243], v139 offset:25600
	ds_read_b128 v[224:227], v180 offset:320
	ds_read_b128 v[228:231], v180 offset:8768
	s_waitcnt lgkmcnt(5)
	v_mfma_f32_16x16x32_bf16 v[118:121], v[204:207], v[200:203], v[118:121]
	v_mfma_f32_16x16x32_bf16 v[114:117], v[204:207], v[210:213], v[114:117]
	ds_read_b128 v[204:207], v139 offset:320
	s_waitcnt lgkmcnt(5)
	v_mfma_f32_16x16x32_bf16 v[110:113], v[232:235], v[200:203], v[110:113]
	v_mfma_f32_16x16x32_bf16 v[106:109], v[232:235], v[210:213], v[106:109]
	ds_read_b128 v[232:235], v139 offset:8768
	s_waitcnt lgkmcnt(5)
	v_mfma_f32_16x16x32_bf16 v[102:105], v[236:239], v[200:203], v[102:105]
	v_mfma_f32_16x16x32_bf16 v[98:101], v[236:239], v[210:213], v[98:101]
	ds_read_b128 v[236:239], v139 offset:17216
	s_waitcnt lgkmcnt(5)
	v_mfma_f32_16x16x32_bf16 v[94:97], v[240:243], v[200:203], v[94:97]
	v_mfma_f32_16x16x32_bf16 v[88:91], v[240:243], v[210:213], v[90:93]
	ds_read_b128 v[240:243], v139 offset:25664
	ds_read_b128 v[200:203], v180 offset:384
	ds_read_b128 v[210:213], v180 offset:8832
	s_waitcnt lgkmcnt(5)
	v_mfma_f32_16x16x32_bf16 v[118:121], v[204:207], v[224:227], v[118:121]
	v_mfma_f32_16x16x32_bf16 v[114:117], v[204:207], v[228:231], v[114:117]
	ds_read_b128 v[204:207], v139 offset:384
	s_waitcnt lgkmcnt(5)
	v_mfma_f32_16x16x32_bf16 v[110:113], v[232:235], v[224:227], v[110:113]
	v_mfma_f32_16x16x32_bf16 v[106:109], v[232:235], v[228:231], v[106:109]
	ds_read_b128 v[232:235], v139 offset:8832
	s_waitcnt lgkmcnt(5)
	v_mfma_f32_16x16x32_bf16 v[102:105], v[236:239], v[224:227], v[102:105]
	v_mfma_f32_16x16x32_bf16 v[98:101], v[236:239], v[228:231], v[98:101]
	ds_read_b128 v[236:239], v139 offset:17280
	s_waitcnt lgkmcnt(5)
	v_mfma_f32_16x16x32_bf16 v[94:97], v[240:243], v[224:227], v[94:97]
	v_mfma_f32_16x16x32_bf16 v[90:93], v[240:243], v[228:231], v[88:91]
	ds_read_b128 v[240:243], v139 offset:25728
	ds_read_b128 v[224:227], v180 offset:448
	ds_read_b128 v[228:231], v180 offset:8896
	s_waitcnt lgkmcnt(5)
	v_mfma_f32_16x16x32_bf16 v[118:121], v[204:207], v[200:203], v[118:121]
	v_mfma_f32_16x16x32_bf16 v[114:117], v[204:207], v[210:213], v[114:117]
	ds_read_b128 v[204:207], v139 offset:448
	s_waitcnt lgkmcnt(5)
	v_mfma_f32_16x16x32_bf16 v[110:113], v[232:235], v[200:203], v[110:113]
	v_mfma_f32_16x16x32_bf16 v[106:109], v[232:235], v[210:213], v[106:109]
	ds_read_b128 v[232:235], v139 offset:8896
	s_waitcnt lgkmcnt(5)
	v_mfma_f32_16x16x32_bf16 v[102:105], v[236:239], v[200:203], v[102:105]
	v_mfma_f32_16x16x32_bf16 v[98:101], v[236:239], v[210:213], v[98:101]
	ds_read_b128 v[236:239], v139 offset:17344
	s_waitcnt lgkmcnt(5)
	v_mfma_f32_16x16x32_bf16 v[94:97], v[240:243], v[200:203], v[94:97]
	v_mfma_f32_16x16x32_bf16 v[88:91], v[240:243], v[210:213], v[90:93]
	ds_read_b128 v[240:243], v139 offset:25792
	s_waitcnt lgkmcnt(3)
	v_mfma_f32_16x16x32_bf16 v[118:121], v[204:207], v[224:227], v[118:121]
	v_mfma_f32_16x16x32_bf16 v[114:117], v[204:207], v[228:231], v[114:117]
	s_waitcnt lgkmcnt(2)
	v_mfma_f32_16x16x32_bf16 v[110:113], v[232:235], v[224:227], v[110:113]
	v_mfma_f32_16x16x32_bf16 v[106:109], v[232:235], v[228:231], v[106:109]
	s_waitcnt lgkmcnt(1)
	v_mfma_f32_16x16x32_bf16 v[102:105], v[236:239], v[224:227], v[102:105]
	v_mfma_f32_16x16x32_bf16 v[98:101], v[236:239], v[228:231], v[98:101]
	s_waitcnt lgkmcnt(0)
	v_mfma_f32_16x16x32_bf16 v[94:97], v[240:243], v[224:227], v[94:97]
	v_mfma_f32_16x16x32_bf16 v[90:93], v[240:243], v[228:231], v[88:91]
	v_mov_b32_e32 v133, v131
	s_mov_b32 s0, 0x42fc0000
	s_barrier
	s_nop 0
	v_cmp_lt_f32_e32 vcc, s0, v133
	s_mov_b32 s0, 0
	s_nop 0
	v_cndmask_b32_e32 v88, 0, v198, vcc
	v_sub_f32_e32 v88, v88, v133
	v_exp_f32_e32 v135, v88
	v_mul_f32_e32 v88, v133, v159
	v_cndmask_b32_e32 v89, 0, v197, vcc
	v_cmp_gt_f32_e32 vcc, s96, v88
	v_ldexp_f32 v89, v135, v89
	s_nop 0
	v_cndmask_b32_e32 v88, 0, v198, vcc
	v_fmac_f32_e32 v88, v133, v159
	v_exp_f32_e32 v139, v88
	v_cndmask_b32_e32 v137, 0, v197, vcc
	v_mov_b32_e32 v88, 0
	v_ldexp_f32 v200, v139, v137
	v_mul_f32_e32 v118, v118, v200
	v_mul_f32_e32 v135, v89, v200
	v_cndmask_b32_e64 v118, v118, 0, s[16:17]
	v_mul_f32_e32 v119, v119, v135
	v_cndmask_b32_e64 v119, 0, v119, s[18:19]
	v_bfe_u32 v135, v118, 16, 1
	v_add3_u32 v118, v118, v135, s3
	v_bfe_u32 v135, v119, 16, 1
	v_lshrrev_b32_e32 v118, 16, v118
	v_add3_u32 v119, v119, v135, s3
	v_and_or_b32 v202, v119, s88, v118
	v_mul_f32_e32 v118, v89, v89
	v_mul_f32_e32 v119, v89, v118
	v_pk_mul_f32 v[200:201], v[200:201], v[118:119] op_sel_hi:[0,1]
	v_pk_mul_f32 v[120:121], v[120:121], v[200:201]
	s_nop 0
	v_cndmask_b32_e64 v121, v121, 0, s[20:21]
	v_and_b32_sdwa v135, v121, v199 dst_sel:DWORD dst_unused:UNUSED_PAD src0_sel:WORD_1 src1_sel:DWORD
	v_cndmask_b32_e64 v120, v120, 0, s[22:23]
	v_add3_u32 v121, v121, v135, s3
	v_mul_f32_e32 v135, v133, v157
	v_and_b32_sdwa v137, v120, v199 dst_sel:DWORD dst_unused:UNUSED_PAD src0_sel:WORD_1 src1_sel:DWORD
	v_cmp_gt_f32_e32 vcc, s96, v135
	v_add3_u32 v120, v120, v137, s3
	v_lshrrev_b32_e32 v120, 16, v120
	v_cndmask_b32_e32 v137, 0, v198, vcc
	v_fmac_f32_e32 v137, v133, v157
	v_exp_f32_e32 v137, v137
	v_cndmask_b32_e32 v135, 0, v197, vcc
	v_and_or_b32 v203, v121, s88, v120
	v_add_u32_e32 v120, v156, v160
	ds_write_b64 v120, v[202:203]
	v_ldexp_f32 v120, v137, v135
	v_mul_f32_e32 v121, v89, v120
	v_mul_f32_e32 v135, v115, v121
	v_mul_f32_e32 v115, v120, v119
	v_mul_f32_e32 v121, v118, v120
	v_mul_f32_e32 v117, v117, v115
	v_mov_b32_e32 v115, v116
	v_pk_mul_f32 v[114:115], v[114:115], v[120:121]
	v_cndmask_b32_e64 v116, v117, 0, s[14:15]
	v_cndmask_b32_e64 v115, v115, 0, s[10:11]
	v_and_b32_sdwa v120, v115, v199 dst_sel:DWORD dst_unused:UNUSED_PAD src0_sel:WORD_1 src1_sel:DWORD
	v_add3_u32 v115, v115, v120, s3
	v_and_b32_sdwa v120, v116, v199 dst_sel:DWORD dst_unused:UNUSED_PAD src0_sel:WORD_1 src1_sel:DWORD
	v_add3_u32 v116, v116, v120, s3
	v_and_b32_e32 v116, 0xffff0000, v116
	v_or_b32_sdwa v115, v116, v115 dst_sel:DWORD dst_unused:UNUSED_PAD src0_sel:DWORD src1_sel:WORD_1
	v_mul_f32_e32 v116, v133, v162
	v_cmp_gt_f32_e32 vcc, s96, v116
	v_cndmask_b32_e64 v114, v114, 0, s[8:9]
	v_cndmask_b32_e64 v117, 0, v135, s[12:13]
	v_cndmask_b32_e32 v120, 0, v198, vcc
	v_and_b32_sdwa v121, v114, v199 dst_sel:DWORD dst_unused:UNUSED_PAD src0_sel:WORD_1 src1_sel:DWORD
	v_fmac_f32_e32 v120, v133, v162
	v_add3_u32 v114, v114, v121, s3
	v_and_b32_sdwa v121, v117, v199 dst_sel:DWORD dst_unused:UNUSED_PAD src0_sel:WORD_1 src1_sel:DWORD
	v_exp_f32_e32 v120, v120
	v_add3_u32 v117, v117, v121, s3
	v_and_b32_e32 v117, 0xffff0000, v117
	v_cndmask_b32_e32 v116, 0, v197, vcc
	v_or_b32_sdwa v114, v117, v114 dst_sel:DWORD dst_unused:UNUSED_PAD src0_sel:DWORD src1_sel:WORD_1
	v_add_u32_e32 v117, v156, v158
	ds_write_b64 v117, v[114:115]
	v_ldexp_f32 v114, v120, v116
	v_mul_f32_e32 v115, v89, v114
	v_mul_f32_e32 v116, v111, v115
	v_mul_f32_e32 v111, v114, v119
	v_mul_f32_e32 v115, v118, v114
	v_mul_f32_e32 v113, v113, v111
	v_mov_b32_e32 v111, v112
	v_pk_mul_f32 v[110:111], v[110:111], v[114:115]
	v_cndmask_b32_e64 v112, v113, 0, s[28:29]
	v_cndmask_b32_e64 v111, v111, 0, s[24:25]
	v_and_b32_sdwa v114, v111, v199 dst_sel:DWORD dst_unused:UNUSED_PAD src0_sel:WORD_1 src1_sel:DWORD
	v_add3_u32 v111, v111, v114, s3
	v_and_b32_sdwa v114, v112, v199 dst_sel:DWORD dst_unused:UNUSED_PAD src0_sel:WORD_1 src1_sel:DWORD
	v_add3_u32 v112, v112, v114, s3
	v_and_b32_e32 v112, 0xffff0000, v112
	v_or_b32_sdwa v111, v112, v111 dst_sel:DWORD dst_unused:UNUSED_PAD src0_sel:DWORD src1_sel:WORD_1
	v_mul_f32_e32 v112, v133, v163
	v_cmp_gt_f32_e32 vcc, s96, v112
	v_cndmask_b32_e64 v110, v110, 0, s[26:27]
	v_cndmask_b32_e64 v113, 0, v116, s[30:31]
	v_cndmask_b32_e32 v114, 0, v198, vcc
	v_and_b32_sdwa v115, v110, v199 dst_sel:DWORD dst_unused:UNUSED_PAD src0_sel:WORD_1 src1_sel:DWORD
	v_fmac_f32_e32 v114, v133, v163
	v_add3_u32 v110, v110, v115, s3
	v_and_b32_sdwa v115, v113, v199 dst_sel:DWORD dst_unused:UNUSED_PAD src0_sel:WORD_1 src1_sel:DWORD
	v_exp_f32_e32 v114, v114
	v_add3_u32 v113, v113, v115, s3
	v_and_b32_e32 v113, 0xffff0000, v113
	v_cndmask_b32_e32 v112, 0, v197, vcc
	v_or_b32_sdwa v110, v113, v110 dst_sel:DWORD dst_unused:UNUSED_PAD src0_sel:DWORD src1_sel:WORD_1
	v_add_u32_e32 v113, v161, v160
	ds_write_b64 v113, v[110:111]
	v_ldexp_f32 v110, v114, v112
	v_mul_f32_e32 v111, v89, v110
	v_mul_f32_e32 v112, v107, v111
	v_mul_f32_e32 v107, v110, v119
	v_mul_f32_e32 v111, v118, v110
	v_mul_f32_e32 v109, v109, v107
	v_mov_b32_e32 v107, v108
	v_pk_mul_f32 v[106:107], v[106:107], v[110:111]
	v_cndmask_b32_e64 v108, v109, 0, s[38:39]
	v_cndmask_b32_e64 v107, v107, 0, s[34:35]
	v_and_b32_sdwa v110, v107, v199 dst_sel:DWORD dst_unused:UNUSED_PAD src0_sel:WORD_1 src1_sel:DWORD
	v_add3_u32 v107, v107, v110, s3
	v_and_b32_sdwa v110, v108, v199 dst_sel:DWORD dst_unused:UNUSED_PAD src0_sel:WORD_1 src1_sel:DWORD
	v_add3_u32 v108, v108, v110, s3
	v_and_b32_e32 v108, 0xffff0000, v108
	v_or_b32_sdwa v107, v108, v107 dst_sel:DWORD dst_unused:UNUSED_PAD src0_sel:DWORD src1_sel:WORD_1
	v_mul_f32_e32 v108, v133, v165
	v_cmp_gt_f32_e32 vcc, s96, v108
	v_cndmask_b32_e64 v106, v106, 0, s[36:37]
	v_cndmask_b32_e64 v109, 0, v112, s[40:41]
	v_cndmask_b32_e32 v110, 0, v198, vcc
	v_and_b32_sdwa v111, v106, v199 dst_sel:DWORD dst_unused:UNUSED_PAD src0_sel:WORD_1 src1_sel:DWORD
	v_fmac_f32_e32 v110, v133, v165
	v_add3_u32 v106, v106, v111, s3
	v_and_b32_sdwa v111, v109, v199 dst_sel:DWORD dst_unused:UNUSED_PAD src0_sel:WORD_1 src1_sel:DWORD
	v_exp_f32_e32 v110, v110
	v_add3_u32 v109, v109, v111, s3
	v_and_b32_e32 v109, 0xffff0000, v109
	v_cndmask_b32_e32 v108, 0, v197, vcc
	v_or_b32_sdwa v106, v109, v106 dst_sel:DWORD dst_unused:UNUSED_PAD src0_sel:DWORD src1_sel:WORD_1
	v_add_u32_e32 v109, v161, v158
	ds_write_b64 v109, v[106:107]
	v_ldexp_f32 v106, v110, v108
	v_mul_f32_e32 v107, v89, v106
	v_mul_f32_e32 v108, v103, v107
	v_mul_f32_e32 v103, v106, v119
	v_mul_f32_e32 v107, v118, v106
	v_mul_f32_e32 v105, v105, v103
	v_mov_b32_e32 v103, v104
	v_pk_mul_f32 v[102:103], v[102:103], v[106:107]
	v_cndmask_b32_e64 v104, v105, 0, s[48:49]
	v_cndmask_b32_e64 v103, v103, 0, s[42:43]
	v_and_b32_sdwa v106, v103, v199 dst_sel:DWORD dst_unused:UNUSED_PAD src0_sel:WORD_1 src1_sel:DWORD
	v_add3_u32 v103, v103, v106, s3
	v_and_b32_sdwa v106, v104, v199 dst_sel:DWORD dst_unused:UNUSED_PAD src0_sel:WORD_1 src1_sel:DWORD
	v_add3_u32 v104, v104, v106, s3
	v_and_b32_e32 v104, 0xffff0000, v104
	v_or_b32_sdwa v103, v104, v103 dst_sel:DWORD dst_unused:UNUSED_PAD src0_sel:DWORD src1_sel:WORD_1
	v_mul_f32_e32 v104, v133, v166
	v_cmp_gt_f32_e32 vcc, s96, v104
	v_cndmask_b32_e64 v102, v102, 0, s[44:45]
	v_cndmask_b32_e64 v105, 0, v108, s[46:47]
	v_cndmask_b32_e32 v106, 0, v198, vcc
	v_and_b32_sdwa v107, v102, v199 dst_sel:DWORD dst_unused:UNUSED_PAD src0_sel:WORD_1 src1_sel:DWORD
	v_fmac_f32_e32 v106, v133, v166
	v_add3_u32 v102, v102, v107, s3
	v_and_b32_sdwa v107, v105, v199 dst_sel:DWORD dst_unused:UNUSED_PAD src0_sel:WORD_1 src1_sel:DWORD
	v_exp_f32_e32 v106, v106
	v_add3_u32 v105, v105, v107, s3
	v_and_b32_e32 v105, 0xffff0000, v105
	v_cndmask_b32_e32 v104, 0, v197, vcc
	v_or_b32_sdwa v102, v105, v102 dst_sel:DWORD dst_unused:UNUSED_PAD src0_sel:DWORD src1_sel:WORD_1
	v_add_u32_e32 v105, v164, v160
	ds_write_b64 v105, v[102:103]
	v_ldexp_f32 v102, v106, v104
	v_mul_f32_e32 v103, v89, v102
	v_mul_f32_e32 v104, v99, v103
	v_mul_f32_e32 v99, v102, v119
	v_mul_f32_e32 v103, v118, v102
	v_mul_f32_e32 v101, v101, v99
	v_mov_b32_e32 v99, v100
	v_pk_mul_f32 v[98:99], v[98:99], v[102:103]
	v_cndmask_b32_e64 v100, v101, 0, s[54:55]
	v_cndmask_b32_e64 v99, v99, 0, s[50:51]
	v_and_b32_sdwa v102, v99, v199 dst_sel:DWORD dst_unused:UNUSED_PAD src0_sel:WORD_1 src1_sel:DWORD
	v_add3_u32 v99, v99, v102, s3
	v_and_b32_sdwa v102, v100, v199 dst_sel:DWORD dst_unused:UNUSED_PAD src0_sel:WORD_1 src1_sel:DWORD
	v_add3_u32 v100, v100, v102, s3
	v_and_b32_e32 v100, 0xffff0000, v100
	v_or_b32_sdwa v99, v100, v99 dst_sel:DWORD dst_unused:UNUSED_PAD src0_sel:DWORD src1_sel:WORD_1
	v_mul_f32_e32 v100, v133, v168
	v_cmp_gt_f32_e32 vcc, s96, v100
	v_cndmask_b32_e64 v98, v98, 0, s[52:53]
	v_cndmask_b32_e64 v101, 0, v104, s[56:57]
	v_cndmask_b32_e32 v102, 0, v198, vcc
	v_and_b32_sdwa v103, v98, v199 dst_sel:DWORD dst_unused:UNUSED_PAD src0_sel:WORD_1 src1_sel:DWORD
	v_fmac_f32_e32 v102, v133, v168
	v_add3_u32 v98, v98, v103, s3
	v_and_b32_sdwa v103, v101, v199 dst_sel:DWORD dst_unused:UNUSED_PAD src0_sel:WORD_1 src1_sel:DWORD
	v_exp_f32_e32 v102, v102
	v_add3_u32 v101, v101, v103, s3
	v_and_b32_e32 v101, 0xffff0000, v101
	v_cndmask_b32_e32 v100, 0, v197, vcc
	v_or_b32_sdwa v98, v101, v98 dst_sel:DWORD dst_unused:UNUSED_PAD src0_sel:DWORD src1_sel:WORD_1
	v_add_u32_e32 v101, v164, v158
	ds_write_b64 v101, v[98:99]
	v_ldexp_f32 v98, v102, v100
	v_mul_f32_e32 v99, v89, v98
	v_mul_f32_e32 v100, v95, v99
	v_mul_f32_e32 v95, v98, v119
	v_mul_f32_e32 v99, v118, v98
	v_mul_f32_e32 v97, v97, v95
	v_mov_b32_e32 v95, v96
	v_pk_mul_f32 v[94:95], v[94:95], v[98:99]
	v_cndmask_b32_e64 v96, v97, 0, s[64:65]
	v_cndmask_b32_e64 v95, v95, 0, s[58:59]
	v_and_b32_sdwa v98, v95, v199 dst_sel:DWORD dst_unused:UNUSED_PAD src0_sel:WORD_1 src1_sel:DWORD
	v_add3_u32 v95, v95, v98, s3
	v_and_b32_sdwa v98, v96, v199 dst_sel:DWORD dst_unused:UNUSED_PAD src0_sel:WORD_1 src1_sel:DWORD
	v_add3_u32 v96, v96, v98, s3
	v_and_b32_e32 v96, 0xffff0000, v96
	v_or_b32_sdwa v95, v96, v95 dst_sel:DWORD dst_unused:UNUSED_PAD src0_sel:DWORD src1_sel:WORD_1
	v_mul_f32_e32 v96, v133, v169
	v_cmp_gt_f32_e32 vcc, s96, v96
	v_cndmask_b32_e64 v94, v94, 0, s[60:61]
	v_cndmask_b32_e64 v97, 0, v100, s[62:63]
	v_cndmask_b32_e32 v98, 0, v198, vcc
	v_and_b32_sdwa v99, v94, v199 dst_sel:DWORD dst_unused:UNUSED_PAD src0_sel:WORD_1 src1_sel:DWORD
	v_fmac_f32_e32 v98, v133, v169
	v_add3_u32 v94, v94, v99, s3
	v_and_b32_sdwa v99, v97, v199 dst_sel:DWORD dst_unused:UNUSED_PAD src0_sel:WORD_1 src1_sel:DWORD
	v_exp_f32_e32 v98, v98
	v_add3_u32 v97, v97, v99, s3
	v_and_b32_e32 v97, 0xffff0000, v97
	v_cndmask_b32_e32 v96, 0, v197, vcc
	v_or_b32_sdwa v94, v97, v94 dst_sel:DWORD dst_unused:UNUSED_PAD src0_sel:DWORD src1_sel:WORD_1
	v_add_u32_e32 v97, v167, v160
	ds_write_b64 v97, v[94:95]
	v_ldexp_f32 v94, v98, v96
	v_mul_f32_e32 v89, v89, v94
	v_mul_f32_e32 v89, v91, v89
	v_mul_f32_e32 v91, v94, v119
	v_mul_f32_e32 v95, v118, v94
	v_mul_f32_e32 v93, v93, v91
	v_mov_b32_e32 v91, v92
	v_pk_mul_f32 v[90:91], v[90:91], v[94:95]
	v_cndmask_b32_e64 v92, v93, 0, s[70:71]
	v_cndmask_b32_e64 v90, v90, 0, s[68:69]
	v_cndmask_b32_e64 v91, v91, 0, s[66:67]
	v_cndmask_b32_e64 v89, 0, v89, s[72:73]
	v_and_b32_sdwa v93, v91, v199 dst_sel:DWORD dst_unused:UNUSED_PAD src0_sel:WORD_1 src1_sel:DWORD
	v_and_b32_sdwa v94, v90, v199 dst_sel:DWORD dst_unused:UNUSED_PAD src0_sel:WORD_1 src1_sel:DWORD
	v_add3_u32 v90, v90, v94, s3
	v_add3_u32 v91, v91, v93, s3
	v_and_b32_sdwa v93, v92, v199 dst_sel:DWORD dst_unused:UNUSED_PAD src0_sel:WORD_1 src1_sel:DWORD
	v_and_b32_sdwa v94, v89, v199 dst_sel:DWORD dst_unused:UNUSED_PAD src0_sel:WORD_1 src1_sel:DWORD
	v_add3_u32 v92, v92, v93, s3
	v_add3_u32 v89, v89, v94, s3
	v_and_b32_e32 v92, 0xffff0000, v92
	v_and_b32_e32 v89, 0xffff0000, v89
	v_or_b32_sdwa v91, v92, v91 dst_sel:DWORD dst_unused:UNUSED_PAD src0_sel:DWORD src1_sel:WORD_1
	v_or_b32_sdwa v90, v89, v90 dst_sel:DWORD dst_unused:UNUSED_PAD src0_sel:DWORD src1_sel:WORD_1
	v_add_u32_e32 v89, v167, v158
	ds_write_b64 v89, v[90:91]
	v_bfe_u32 v89, v84, 16, 1
	v_add3_u32 v89, v84, v89, s3
	v_bfe_u32 v90, v85, 16, 1
	v_lshrrev_b32_e32 v89, 16, v89
	v_add3_u32 v90, v85, v90, s3
	v_and_or_b32 v90, v90, s88, v89
	v_bfe_u32 v89, v86, 16, 1
	v_add3_u32 v89, v86, v89, s3
	v_bfe_u32 v91, v87, 16, 1
	v_lshrrev_b32_e32 v89, 16, v89
	v_add3_u32 v91, v87, v91, s3
	v_and_or_b32 v91, v91, s88, v89
	v_add_u32_e32 v89, v146, v153
	ds_write_b64 v89, v[90:91]
	v_bfe_u32 v90, v80, 16, 1
	v_add3_u32 v90, v80, v90, s3
	v_bfe_u32 v91, v81, 16, 1
	v_lshrrev_b32_e32 v90, 16, v90
	v_add3_u32 v91, v81, v91, s3
	v_and_or_b32 v90, v91, s88, v90
	v_bfe_u32 v91, v82, 16, 1
	v_add3_u32 v91, v82, v91, s3
	v_bfe_u32 v92, v83, 16, 1
	v_lshrrev_b32_e32 v91, 16, v91
	v_add3_u32 v92, v83, v92, s3
	v_and_or_b32 v91, v92, s88, v91
	ds_write_b64 v191, v[90:91]
	v_bfe_u32 v90, v76, 16, 1
	v_add3_u32 v90, v76, v90, s3
	v_bfe_u32 v91, v77, 16, 1
	v_lshrrev_b32_e32 v90, 16, v90
	v_add3_u32 v91, v77, v91, s3
	v_and_or_b32 v90, v91, s88, v90
	v_bfe_u32 v91, v78, 16, 1
	v_add3_u32 v91, v78, v91, s3
	v_bfe_u32 v92, v79, 16, 1
	v_lshrrev_b32_e32 v91, 16, v91
	v_add3_u32 v92, v79, v92, s3
	v_and_or_b32 v91, v92, s88, v91
	ds_write_b64 v89, v[90:91] offset:32
	v_bfe_u32 v89, v68, 16, 1
	v_add3_u32 v89, v68, v89, s3
	v_bfe_u32 v90, v69, 16, 1
	v_lshrrev_b32_e32 v89, 16, v89
	v_add3_u32 v90, v69, v90, s3
	v_and_or_b32 v90, v90, s88, v89
	v_bfe_u32 v89, v70, 16, 1
	v_add3_u32 v89, v70, v89, s3
	v_bfe_u32 v91, v71, 16, 1
	v_lshrrev_b32_e32 v89, 16, v89
	v_add3_u32 v91, v71, v91, s3
	v_and_or_b32 v91, v91, s88, v89
	ds_write_b64 v191, v[90:91] offset:32
	v_mov_b32_e32 v89, v88
	v_mov_b32_e32 v90, v88
	v_mov_b32_e32 v91, v88
	v_mov_b32_e32 v96, v88
	v_mov_b32_e32 v97, v88
	v_mov_b32_e32 v98, v88
	v_mov_b32_e32 v99, v88
	s_waitcnt lgkmcnt(0)
	s_barrier
.LBB0_698:
	v_add_u32_e32 v139, 0x10800, v183
	v_add_u32_e32 v135, 0x21800, v182
	ds_read_b128 v[92:95], v139
	ds_read_b128 v[100:103], v135
	ds_read_b128 v[104:107], v135 offset:4352
	ds_read_b128 v[200:203], v139 offset:64
	ds_read_b128 v[204:207], v135 offset:64
	ds_read_b128 v[210:213], v135 offset:4416
	ds_read_b128 v[220:223], v139 offset:128
	ds_read_b128 v[224:227], v135 offset:128
	ds_read_b128 v[228:231], v135 offset:4480
	ds_read_b128 v[232:235], v139 offset:192
	ds_read_b128 v[236:239], v135 offset:192
	ds_read_b128 v[240:243], v135 offset:4544
	s_waitcnt lgkmcnt(10)
	v_mfma_f32_16x16x32_bf16 v[96:99], v[92:95], v[100:103], v[96:99]
	s_waitcnt lgkmcnt(9)
	v_mfma_f32_16x16x32_bf16 v[88:91], v[92:95], v[104:107], v[88:91]
	s_waitcnt lgkmcnt(7)
	v_mfma_f32_16x16x32_bf16 v[96:99], v[200:203], v[204:207], v[96:99]
	s_waitcnt lgkmcnt(6)
	v_mfma_f32_16x16x32_bf16 v[88:91], v[200:203], v[210:213], v[88:91]
	s_waitcnt lgkmcnt(4)
	v_mfma_f32_16x16x32_bf16 v[96:99], v[220:223], v[224:227], v[96:99]
	s_waitcnt lgkmcnt(3)
	v_mfma_f32_16x16x32_bf16 v[88:91], v[220:223], v[228:231], v[88:91]
	s_waitcnt lgkmcnt(1)
	v_mfma_f32_16x16x32_bf16 v[96:99], v[232:235], v[236:239], v[96:99]
	s_waitcnt lgkmcnt(0)
	v_mfma_f32_16x16x32_bf16 v[88:91], v[232:235], v[240:243], v[88:91]
	v_mov_b32_e32 v92, 0
	s_mov_b32 s0, 0
	v_mov_b32_e32 v93, v92
	v_mov_b32_e32 v94, v92
	v_mov_b32_e32 v95, v92
	v_mov_b32_e32 v100, v92
	v_mov_b32_e32 v101, v92
	v_mov_b32_e32 v102, v92
	v_mov_b32_e32 v103, v92
.LBB0_700:
	v_add_u32_e32 v137, 0x19000, v154
	ds_read_b128 v[104:107], v155
	ds_read_b128 v[108:111], v137
	ds_read_b128 v[112:115], v137 offset:8448
	ds_read_b128 v[200:203], v155 offset:64
	ds_read_b128 v[204:207], v137 offset:64
	ds_read_b128 v[210:213], v137 offset:8512
	ds_read_b128 v[220:223], v155 offset:128
	ds_read_b128 v[224:227], v137 offset:128
	ds_read_b128 v[228:231], v137 offset:8576
	ds_read_b128 v[232:235], v155 offset:192
	ds_read_b128 v[236:239], v137 offset:192
	ds_read_b128 v[240:243], v137 offset:8640
	s_waitcnt lgkmcnt(10)
	v_mfma_f32_16x16x32_bf16 v[100:103], v[104:107], v[108:111], v[100:103]
	ds_read_b128 v[108:111], v155 offset:256
	s_waitcnt lgkmcnt(10)
	v_mfma_f32_16x16x32_bf16 v[92:95], v[104:107], v[112:115], v[92:95]
	ds_read_b128 v[104:107], v137 offset:256
	ds_read_b128 v[112:115], v137 offset:8704
	s_waitcnt lgkmcnt(10)
	v_mfma_f32_16x16x32_bf16 v[100:103], v[200:203], v[204:207], v[100:103]
	ds_read_b128 v[204:207], v155 offset:320
	s_waitcnt lgkmcnt(10)
	v_mfma_f32_16x16x32_bf16 v[92:95], v[200:203], v[210:213], v[92:95]
	ds_read_b128 v[200:203], v137 offset:320
	ds_read_b128 v[210:213], v137 offset:8768
	s_waitcnt lgkmcnt(10)
	v_mfma_f32_16x16x32_bf16 v[100:103], v[220:223], v[224:227], v[100:103]
	ds_read_b128 v[224:227], v155 offset:384
	s_waitcnt lgkmcnt(10)
	v_mfma_f32_16x16x32_bf16 v[92:95], v[220:223], v[228:231], v[92:95]
	ds_read_b128 v[220:223], v137 offset:384
	ds_read_b128 v[228:231], v137 offset:8832
	s_waitcnt lgkmcnt(10)
	v_mfma_f32_16x16x32_bf16 v[100:103], v[232:235], v[236:239], v[100:103]
	ds_read_b128 v[236:239], v155 offset:448
	s_waitcnt lgkmcnt(10)
	v_mfma_f32_16x16x32_bf16 v[92:95], v[232:235], v[240:243], v[92:95]
	ds_read_b128 v[232:235], v137 offset:448
	ds_read_b128 v[240:243], v137 offset:8896
	s_waitcnt lgkmcnt(10)
	v_mfma_f32_16x16x32_bf16 v[100:103], v[108:111], v[104:107], v[100:103]
	s_waitcnt lgkmcnt(9)
	v_mfma_f32_16x16x32_bf16 v[92:95], v[108:111], v[112:115], v[92:95]
	s_waitcnt lgkmcnt(7)
	v_mfma_f32_16x16x32_bf16 v[100:103], v[204:207], v[200:203], v[100:103]
	s_waitcnt lgkmcnt(6)
	v_mfma_f32_16x16x32_bf16 v[92:95], v[204:207], v[210:213], v[92:95]
	s_waitcnt lgkmcnt(4)
	v_mfma_f32_16x16x32_bf16 v[100:103], v[224:227], v[220:223], v[100:103]
	s_waitcnt lgkmcnt(3)
	v_mfma_f32_16x16x32_bf16 v[92:95], v[224:227], v[228:231], v[92:95]
	s_waitcnt lgkmcnt(1)
	v_mfma_f32_16x16x32_bf16 v[100:103], v[236:239], v[232:235], v[100:103]
	s_waitcnt lgkmcnt(0)
	v_mfma_f32_16x16x32_bf16 v[92:95], v[236:239], v[240:243], v[92:95]
	s_lshl_b32 s97, s80, 7
	s_add_i32 s0, s97, 0xffffff90
	s_cmp_eq_u32 s80, 0
	s_cselect_b32 s86, 0, s0
	s_cselect_b32 s2, 16, 0x80
	s_add_i32 s86, s86, s91
	v_add_u32_e32 v104, s86, v147
	v_cmp_gt_u32_e32 vcc, s2, v147
	v_mul_f32_e32 v108, v133, v171
	v_ashrrev_i32_e32 v105, 31, v104
	s_and_saveexec_b64 s[74:75], vcc
	s_cbranch_execz .LBB0_703
	v_cmp_gt_f32_e64 s[0:1], s96, v108
	s_nop 1
	v_cndmask_b32_e64 v107, 0, v198, s[0:1]
	v_fmac_f32_e32 v107, v133, v171
	v_exp_f32_e32 v107, v107
	v_cndmask_b32_e64 v106, 0, v197, s[0:1]
	v_ldexp_f32 v106, v107, v106
	v_fma_f32 v96, v106, v100, v96
	v_lshlrev_b64 v[106:107], 12, v[104:105]
	v_lshl_add_u64 v[106:107], v[142:143], 0, v[106:107]
	global_store_dword v[106:107], v96, off

.LBB0_713:
	s_or_b64 exec, exec, s[0:1]
	v_add_u32_e32 v88, s2, v148
	v_cvt_f32_i32_e32 v88, v88
	s_barrier
	v_mul_f32_e32 v89, v133, v88
	v_cmp_gt_f32_e32 vcc, s96, v89
	s_cmp_eq_u32 s80, 16
	s_nop 0
	v_cndmask_b32_e32 v89, 0, v198, vcc
	v_fmac_f32_e32 v89, v133, v88
	v_exp_f32_e32 v88, v89
	v_cndmask_b32_e32 v89, 0, v197, vcc
	v_cmp_gt_u32_e32 vcc, s2, v145
	v_ldexp_f32 v88, v88, v89
	s_nop 0
	v_cndmask_b32_e32 v88, 0, v88, vcc
	v_lshlrev_b32_e32 v89, 16, v8
	v_and_b32_e32 v90, 0xffff0000, v8
	v_mul_f32_e32 v89, v88, v89
	v_mul_f32_e32 v90, v88, v90
	v_cvt_pk_bf16_f32 v89, v89, v90
	ds_write_b16 v218, v89
	ds_write_b16_d16_hi v218, v89 offset:272
	v_lshlrev_b32_e32 v89, 16, v9
	v_and_b32_e32 v90, 0xffff0000, v9
	v_mul_f32_e32 v89, v88, v89
	v_mul_f32_e32 v90, v88, v90
	v_cvt_pk_bf16_f32 v89, v89, v90
	ds_write_b16 v218, v89 offset:544
	ds_write_b16_d16_hi v218, v89 offset:816
	v_lshlrev_b32_e32 v89, 16, v10
	v_and_b32_e32 v90, 0xffff0000, v10
	v_mul_f32_e32 v89, v88, v89
	v_mul_f32_e32 v90, v88, v90
	v_cvt_pk_bf16_f32 v89, v89, v90
	ds_write_b16 v218, v89 offset:1088
	ds_write_b16_d16_hi v218, v89 offset:1360
	v_lshlrev_b32_e32 v89, 16, v11
	v_and_b32_e32 v90, 0xffff0000, v11
	v_mul_f32_e32 v89, v88, v89
	v_mul_f32_e32 v90, v88, v90
	v_cvt_pk_bf16_f32 v89, v89, v90
	ds_write_b16 v218, v89 offset:1632
	ds_write_b16_d16_hi v218, v89 offset:1904
	v_lshlrev_b32_e32 v89, 16, v16
	v_and_b32_e32 v90, 0xffff0000, v16
	v_mul_f32_e32 v89, v88, v89
	v_mul_f32_e32 v90, v88, v90
	v_cvt_pk_bf16_f32 v89, v89, v90
	ds_write_b16 v218, v89 offset:2176
	ds_write_b16_d16_hi v218, v89 offset:2448
	v_lshlrev_b32_e32 v89, 16, v17
	v_and_b32_e32 v90, 0xffff0000, v17
	v_mul_f32_e32 v89, v88, v89
	v_mul_f32_e32 v90, v88, v90
	v_cvt_pk_bf16_f32 v89, v89, v90
	ds_write_b16 v218, v89 offset:2720
	ds_write_b16_d16_hi v218, v89 offset:2992
	v_lshlrev_b32_e32 v89, 16, v18
	v_and_b32_e32 v90, 0xffff0000, v18
	v_mul_f32_e32 v89, v88, v89
	v_mul_f32_e32 v90, v88, v90
	v_cvt_pk_bf16_f32 v89, v89, v90
	ds_write_b16 v218, v89 offset:3264
	ds_write_b16_d16_hi v218, v89 offset:3536
	v_lshlrev_b32_e32 v89, 16, v19
	v_and_b32_e32 v90, 0xffff0000, v19
	v_mul_f32_e32 v89, v88, v89
	v_mul_f32_e32 v90, v88, v90
	v_cvt_pk_bf16_f32 v89, v89, v90
	ds_write_b16 v218, v89 offset:3808
	ds_write_b16_d16_hi v218, v89 offset:4080
	v_lshlrev_b32_e32 v89, 16, v24
	v_and_b32_e32 v90, 0xffff0000, v24
	v_mul_f32_e32 v89, v88, v89
	v_mul_f32_e32 v90, v88, v90
	v_cvt_pk_bf16_f32 v89, v89, v90
	ds_write_b16 v218, v89 offset:4352
	ds_write_b16_d16_hi v218, v89 offset:4624
	v_lshlrev_b32_e32 v89, 16, v25
	v_and_b32_e32 v90, 0xffff0000, v25
	v_mul_f32_e32 v89, v88, v89
	v_mul_f32_e32 v90, v88, v90
	v_cvt_pk_bf16_f32 v89, v89, v90
	ds_write_b16 v218, v89 offset:4896
	ds_write_b16_d16_hi v218, v89 offset:5168
	v_lshlrev_b32_e32 v89, 16, v26
	v_and_b32_e32 v90, 0xffff0000, v26
	v_mul_f32_e32 v89, v88, v89
	v_mul_f32_e32 v90, v88, v90
	v_cvt_pk_bf16_f32 v89, v89, v90
	ds_write_b16 v218, v89 offset:5440
	ds_write_b16_d16_hi v218, v89 offset:5712
	v_lshlrev_b32_e32 v89, 16, v27
	v_and_b32_e32 v90, 0xffff0000, v27
	v_mul_f32_e32 v89, v88, v89
	v_mul_f32_e32 v90, v88, v90
	v_cvt_pk_bf16_f32 v89, v89, v90
	ds_write_b16 v218, v89 offset:5984
	ds_write_b16_d16_hi v218, v89 offset:6256
	v_lshlrev_b32_e32 v89, 16, v32
	v_and_b32_e32 v90, 0xffff0000, v32
	v_mul_f32_e32 v89, v88, v89
	v_mul_f32_e32 v90, v88, v90
	v_cvt_pk_bf16_f32 v89, v89, v90
	ds_write_b16 v218, v89 offset:6528
	ds_write_b16_d16_hi v218, v89 offset:6800
	v_lshlrev_b32_e32 v89, 16, v33
	v_and_b32_e32 v90, 0xffff0000, v33
	v_mul_f32_e32 v89, v88, v89
	v_mul_f32_e32 v90, v88, v90
	v_cvt_pk_bf16_f32 v89, v89, v90
	ds_write_b16 v218, v89 offset:7072
	ds_write_b16_d16_hi v218, v89 offset:7344
	v_lshlrev_b32_e32 v89, 16, v34
	v_and_b32_e32 v90, 0xffff0000, v34
	v_mul_f32_e32 v89, v88, v89
	v_mul_f32_e32 v90, v88, v90
	v_cvt_pk_bf16_f32 v89, v89, v90
	ds_write_b16 v218, v89 offset:7616
	ds_write_b16_d16_hi v218, v89 offset:7888
	v_lshlrev_b32_e32 v89, 16, v35
	v_and_b32_e32 v90, 0xffff0000, v35
	v_mul_f32_e32 v89, v88, v89
	v_mul_f32_e32 v90, v88, v90
	v_cvt_pk_bf16_f32 v89, v89, v90
	ds_write_b16 v218, v89 offset:8160
	ds_write_b16_d16_hi v218, v89 offset:8432
	v_lshlrev_b32_e32 v89, 16, v40
	v_and_b32_e32 v90, 0xffff0000, v40
	v_mul_f32_e32 v89, v88, v89
	v_mul_f32_e32 v90, v88, v90
	v_cvt_pk_bf16_f32 v89, v89, v90
	ds_write_b16 v218, v89 offset:8704
	ds_write_b16_d16_hi v218, v89 offset:8976
	v_lshlrev_b32_e32 v89, 16, v41
	v_and_b32_e32 v90, 0xffff0000, v41
	v_mul_f32_e32 v89, v88, v89
	v_mul_f32_e32 v90, v88, v90
	v_cvt_pk_bf16_f32 v89, v89, v90
	ds_write_b16 v218, v89 offset:9248
	ds_write_b16_d16_hi v218, v89 offset:9520
	v_lshlrev_b32_e32 v89, 16, v42
	v_and_b32_e32 v90, 0xffff0000, v42
	v_mul_f32_e32 v89, v88, v89
	v_mul_f32_e32 v90, v88, v90
	v_cvt_pk_bf16_f32 v89, v89, v90
	ds_write_b16 v218, v89 offset:9792
	ds_write_b16_d16_hi v218, v89 offset:10064
	v_lshlrev_b32_e32 v89, 16, v43
	v_and_b32_e32 v90, 0xffff0000, v43
	v_mul_f32_e32 v89, v88, v89
	v_mul_f32_e32 v90, v88, v90
	v_cvt_pk_bf16_f32 v89, v89, v90
	ds_write_b16 v218, v89 offset:10336
	ds_write_b16_d16_hi v218, v89 offset:10608
	v_lshlrev_b32_e32 v89, 16, v48
	v_and_b32_e32 v90, 0xffff0000, v48
	v_mul_f32_e32 v89, v88, v89
	v_mul_f32_e32 v90, v88, v90
	v_cvt_pk_bf16_f32 v89, v89, v90
	ds_write_b16 v218, v89 offset:10880
	ds_write_b16_d16_hi v218, v89 offset:11152
	v_lshlrev_b32_e32 v89, 16, v49
	v_and_b32_e32 v90, 0xffff0000, v49
	v_mul_f32_e32 v89, v88, v89
	v_mul_f32_e32 v90, v88, v90
	v_cvt_pk_bf16_f32 v89, v89, v90
	ds_write_b16 v218, v89 offset:11424
	ds_write_b16_d16_hi v218, v89 offset:11696
	v_lshlrev_b32_e32 v89, 16, v50
	v_and_b32_e32 v90, 0xffff0000, v50
	v_mul_f32_e32 v89, v88, v89
	v_mul_f32_e32 v90, v88, v90
	v_cvt_pk_bf16_f32 v89, v89, v90
	ds_write_b16 v218, v89 offset:11968
	ds_write_b16_d16_hi v218, v89 offset:12240
	v_lshlrev_b32_e32 v89, 16, v51
	v_and_b32_e32 v90, 0xffff0000, v51
	v_mul_f32_e32 v89, v88, v89
	v_mul_f32_e32 v90, v88, v90
	v_cvt_pk_bf16_f32 v89, v89, v90
	ds_write_b16 v218, v89 offset:12512
	ds_write_b16_d16_hi v218, v89 offset:12784
	v_lshlrev_b32_e32 v89, 16, v56
	v_and_b32_e32 v90, 0xffff0000, v56
	v_mul_f32_e32 v89, v88, v89
	v_mul_f32_e32 v90, v88, v90
	v_cvt_pk_bf16_f32 v89, v89, v90
	ds_write_b16 v218, v89 offset:13056
	ds_write_b16_d16_hi v218, v89 offset:13328
	v_lshlrev_b32_e32 v89, 16, v57
	v_and_b32_e32 v90, 0xffff0000, v57
	v_mul_f32_e32 v89, v88, v89
	v_mul_f32_e32 v90, v88, v90
	v_cvt_pk_bf16_f32 v89, v89, v90
	ds_write_b16 v218, v89 offset:13600
	ds_write_b16_d16_hi v218, v89 offset:13872
	v_lshlrev_b32_e32 v89, 16, v58
	v_and_b32_e32 v90, 0xffff0000, v58
	v_mul_f32_e32 v89, v88, v89
	v_mul_f32_e32 v90, v88, v90
	v_cvt_pk_bf16_f32 v89, v89, v90
	ds_write_b16 v218, v89 offset:14144
	ds_write_b16_d16_hi v218, v89 offset:14416
	v_lshlrev_b32_e32 v89, 16, v59
	v_and_b32_e32 v90, 0xffff0000, v59
	v_mul_f32_e32 v89, v88, v89
	v_mul_f32_e32 v90, v88, v90
	v_cvt_pk_bf16_f32 v89, v89, v90
	ds_write_b16 v218, v89 offset:14688
	ds_write_b16_d16_hi v218, v89 offset:14960
	v_lshlrev_b32_e32 v89, 16, v64
	v_and_b32_e32 v90, 0xffff0000, v64
	v_mul_f32_e32 v89, v88, v89
	v_mul_f32_e32 v90, v88, v90
	v_cvt_pk_bf16_f32 v89, v89, v90
	ds_write_b16 v218, v89 offset:15232
	ds_write_b16_d16_hi v218, v89 offset:15504
	v_lshlrev_b32_e32 v89, 16, v65
	v_and_b32_e32 v90, 0xffff0000, v65
	v_mul_f32_e32 v89, v88, v89
	v_mul_f32_e32 v90, v88, v90
	v_cvt_pk_bf16_f32 v89, v89, v90
	ds_write_b16 v218, v89 offset:15776
	ds_write_b16_d16_hi v218, v89 offset:16048
	v_lshlrev_b32_e32 v89, 16, v66
	v_and_b32_e32 v90, 0xffff0000, v66
	v_mul_f32_e32 v89, v88, v89
	v_mul_f32_e32 v90, v88, v90
	v_cvt_pk_bf16_f32 v89, v89, v90
	ds_write_b16 v218, v89 offset:16320
	ds_write_b16_d16_hi v218, v89 offset:16592
	v_lshlrev_b32_e32 v89, 16, v67
	v_and_b32_e32 v90, 0xffff0000, v67
	v_mul_f32_e32 v89, v88, v89
	v_mul_f32_e32 v90, v88, v90
	v_cvt_pk_bf16_f32 v89, v89, v90
	ds_write_b16 v218, v89 offset:16864
	ds_write_b16_d16_hi v218, v89 offset:17136
	s_cbranch_scc1 .LBB0_715
	v_add_u32_e32 v220, s97, v1
	v_ashrrev_i32_e32 v221, 31, v220
	v_lshlrev_b64 v[220:221], 13, v[220:221]
	v_lshl_add_u64 v[220:221], v[2:3], 0, v[220:221]
	v_lshl_add_u64 v[220:221], v[220:221], 0, v[214:215]
	global_load_dwordx4 v[8:11], v[220:221], off offset:2048
	global_load_dwordx4 v[16:19], v[220:221], off offset:2064
	global_load_dwordx4 v[24:27], v[220:221], off offset:2080
	global_load_dwordx4 v[32:35], v[220:221], off offset:2096
	global_load_dwordx4 v[40:43], v[220:221], off offset:2112
	global_load_dwordx4 v[48:51], v[220:221], off offset:2128
	global_load_dwordx4 v[56:59], v[220:221], off offset:2144
	global_load_dwordx4 v[64:67], v[220:221], off offset:2160

.LBB0_716:
	v_add_u32_e32 v139, 0x10800, v184
	v_add_u32_e32 v135, 0x21800, v182
	ds_read_b128 v[88:91], v139
	ds_read_b128 v[92:95], v135
	ds_read_b128 v[96:99], v135 offset:4352
	ds_read_b128 v[200:203], v139 offset:4352
	ds_read_b128 v[204:207], v139 offset:64
	ds_read_b128 v[210:213], v135 offset:64
	ds_read_b128 v[220:223], v135 offset:4416
	ds_read_b128 v[224:227], v139 offset:4416
	ds_read_b128 v[228:231], v139 offset:128
	ds_read_b128 v[232:235], v135 offset:128
	ds_read_b128 v[236:239], v135 offset:4480
	ds_read_b128 v[240:243], v139 offset:4480
	s_waitcnt lgkmcnt(10)
	v_mfma_f32_16x16x32_bf16 v[84:87], v[88:91], v[92:95], v[84:87]
	s_waitcnt lgkmcnt(9)
	v_mfma_f32_16x16x32_bf16 v[80:83], v[88:91], v[96:99], v[80:83]
	ds_read_b128 v[88:91], v139 offset:192
	s_waitcnt lgkmcnt(9)
	v_mfma_f32_16x16x32_bf16 v[76:79], v[200:203], v[92:95], v[76:79]
	ds_read_b128 v[92:95], v135 offset:192
	v_mfma_f32_16x16x32_bf16 v[68:71], v[200:203], v[96:99], v[68:71]
	ds_read_b128 v[200:203], v135 offset:4544
	ds_read_b128 v[96:99], v139 offset:4544
	s_waitcnt lgkmcnt(10)
	v_mfma_f32_16x16x32_bf16 v[84:87], v[204:207], v[210:213], v[84:87]
	s_waitcnt lgkmcnt(9)
	v_mfma_f32_16x16x32_bf16 v[80:83], v[204:207], v[220:223], v[80:83]
	s_waitcnt lgkmcnt(8)
	v_mfma_f32_16x16x32_bf16 v[76:79], v[224:227], v[210:213], v[76:79]
	v_mfma_f32_16x16x32_bf16 v[68:71], v[224:227], v[220:223], v[68:71]
	s_waitcnt lgkmcnt(6)
	v_mfma_f32_16x16x32_bf16 v[84:87], v[228:231], v[232:235], v[84:87]
	s_waitcnt lgkmcnt(5)
	v_mfma_f32_16x16x32_bf16 v[80:83], v[228:231], v[236:239], v[80:83]
	s_waitcnt lgkmcnt(4)
	v_mfma_f32_16x16x32_bf16 v[76:79], v[240:243], v[232:235], v[76:79]
	v_mfma_f32_16x16x32_bf16 v[68:71], v[240:243], v[236:239], v[68:71]
	s_waitcnt lgkmcnt(2)
	v_mfma_f32_16x16x32_bf16 v[84:87], v[88:91], v[92:95], v[84:87]
	s_waitcnt lgkmcnt(1)
	v_mfma_f32_16x16x32_bf16 v[80:83], v[88:91], v[200:203], v[80:83]
	s_waitcnt lgkmcnt(0)
	v_mfma_f32_16x16x32_bf16 v[76:79], v[96:99], v[92:95], v[76:79]
	v_mfma_f32_16x16x32_bf16 v[68:71], v[96:99], v[200:203], v[68:71]
	s_add_i32 s80, s80, 1
	s_cmp_lg_u32 s80, 17
	s_barrier
	s_cbranch_scc1 .LBB0_695
	s_branch .LBB0_668

.LBB0_740:
	v_readlane_b32 s90, v244, 3
	v_readlane_b32 s62, v244, 0
	v_readlane_b32 s58, v245, 58
	v_readlane_b32 s56, v245, 60
	s_bitcmp0_b32 s82, 4
	v_readlane_b32 s88, v244, 7
	v_readlane_b32 s91, v244, 4
	v_readlane_b32 s61, v244, 2
	v_readlane_b32 s63, v244, 1
	v_readlane_b32 s59, v245, 59
	v_readlane_b32 s57, v245, 61
	v_readlane_b32 s60, v244, 8
	s_cbranch_scc1 .LBB0_762
	s_lshl_b32 s0, s92, 3
	s_add_i32 s10, s84, s0
	s_addk_i32 s10, 0x800
	s_cmpk_gt_i32 s10, 0x7fff
	s_cbranch_scc1 .LBB0_762
	s_add_u32 s0, s96, 0xe800000
	s_addc_u32 s1, s97, 0
	s_add_u32 s8, s96, 0x10a40000
	s_addc_u32 s9, s97, 0
	v_readlane_b32 s12, v245, 6
	s_add_u32 s2, s96, 0x2f00000
	v_readlane_b32 s20, v245, 14
	s_addc_u32 s3, s97, 0
	v_readlane_b32 s13, v245, 7
	v_readlane_b32 s14, v245, 8
	v_readlane_b32 s15, v245, 9
	v_readlane_b32 s21, v245, 15
	s_add_u32 s20, s96, 0x17100000
	v_and_b32_e32 v2, 15, v208
	v_readlane_b32 s23, v245, 17
	s_addc_u32 s21, s97, 0
	v_readlane_b32 s12, v245, 0
	s_lshl_b32 s11, s60, 3
	v_mov_b32_e32 v1, 0
	v_lshlrev_b32_e32 v0, 4, v2
	v_readlane_b32 s18, v245, 12
	v_readlane_b32 s19, v245, 13
	v_readlane_b32 s13, v245, 1
	v_readlane_b32 s14, v245, 2
	v_readlane_b32 s15, v245, 3
	s_sub_i32 s23, 0, s11
	s_lshl_b32 s11, s88, 3
	v_readlane_b32 s24, v245, 18
	s_waitcnt vmcnt(0)
	v_lshl_add_u64 v[18:19], s[18:19], 0, v[0:1]
	v_lshl_add_u64 v[0:1], s[14:15], 0, v[0:1]
	s_mov_b64 s[12:13], 0x4ab1200
	s_add_i32 s11, s84, s11
	v_readlane_b32 s25, v245, 19
	v_readlane_b32 s26, v245, 20
	v_lshl_add_u64 v[20:21], v[0:1], 0, s[12:13]
	s_add_i32 s24, s11, 0x800
	s_lshl_b32 s11, s33, 3
	s_lshl_b32 s12, s60, 4
	v_readlane_b32 s22, v245, 16
	v_readlane_b32 s27, v245, 21
	s_sub_i32 s25, s11, s12
	s_lshl_b32 s26, s10, 2
	s_lshl_b32 s10, s33, 6
	s_lshl_b32 s11, s60, 6
	v_lshrrev_b32_e32 v17, 4, v179
	v_lshlrev_b32_e32 v16, 2, v2
	v_cmp_ne_u32_e64 s[4:5], 0, v2
	v_cmp_eq_u32_e64 s[6:7], 0, v2
	s_lshl_b32 s22, s76, 4
	s_sub_i32 s27, s10, s11
	v_readlane_b32 s16, v245, 10
	v_readlane_b32 s17, v245, 11
	s_branch .LBB0_744

.LBB0_798:
	s_bitcmp0_b32 s82, 4
	s_cbranch_scc1 .LBB0_820
	s_lshl_b32 s0, s88, 3
	s_add_i32 s2, s84, s0
	s_cmp_gt_i32 s2, 0x7ff
	s_cbranch_scc1 .LBB0_820
	v_readlane_b32 s4, v245, 6
	s_lshl_b32 s3, s60, 3
	v_readlane_b32 s6, v245, 8
	v_readlane_b32 s7, v245, 9
	s_add_u32 s6, s96, 0xe800000
	v_readlane_b32 s8, v245, 10
	s_addc_u32 s7, s97, 0
	v_readlane_b32 s9, v245, 11
	s_add_u32 s8, s96, 0x10a40000
	v_readlane_b32 s12, v245, 14
	v_readlane_b32 s13, v245, 15
	v_readlane_b32 s14, v245, 16
	v_readlane_b32 s15, v245, 17
	s_addc_u32 s9, s97, 0
	s_add_u32 s20, s96, 0x2f00000
	v_readlane_b32 s12, v245, 0
	s_waitcnt vmcnt(5)
	v_mov_b32_e32 v1, 0
	v_lshlrev_b32_e32 v0, 4, v70
	v_readlane_b32 s10, v245, 12
	v_readlane_b32 s11, v245, 13
	s_addc_u32 s21, s97, 0
	v_readlane_b32 s14, v245, 2
	v_readlane_b32 s15, v245, 3
	v_lshl_add_u64 v[18:19], s[10:11], 0, v[0:1]
	s_add_u32 s22, s96, 0x17100000
	v_lshl_add_u64 v[0:1], s[14:15], 0, v[0:1]
	s_mov_b64 s[10:11], 0x4ab1200
	v_readlane_b32 s5, v245, 7
	s_addc_u32 s23, s97, 0
	s_waitcnt vmcnt(4)
	v_lshl_add_u64 v[20:21], v[0:1], 0, s[10:11]
	s_lshl_b32 s10, s88, 5
	s_lshl_b32 s11, s84, 2
	v_lshlrev_b32_e32 v16, 2, v70
	v_cmp_ne_u32_e64 s[0:1], 0, v70
	v_cmp_eq_u32_e64 s[4:5], 0, v70
	s_lshl_b32 s24, s60, 4
	s_add_i32 s25, s10, s11
	s_lshl_b32 s26, s60, 6
	v_readlane_b32 s16, v245, 18
	v_readlane_b32 s17, v245, 19
	v_readlane_b32 s18, v245, 20
	v_readlane_b32 s19, v245, 21
	v_readlane_b32 s13, v245, 1
	s_branch .LBB0_802
.LBB0_801:
	s_add_i32 s2, s2, s24
	s_add_i32 s25, s25, s26
	s_cmp_gt_i32 s2, 0x7ff
	s_cbranch_scc1 .LBB0_820
.LBB0_802:
	s_ashr_i32 s29, s2, 8
	s_lshl_b32 s10, s29, 10
	s_and_b32 s28, s25, 0x3c0
	v_readlane_b32 s36, v245, 6
	s_or_b32 s34, s28, s10
	s_mul_i32 s11, s29, 0x3480
	v_readlane_b32 s40, v245, 10
	s_mul_hi_i32 s10, s29, 0x3480
	v_readlane_b32 s41, v245, 11
	s_add_u32 s14, s40, s11
	s_addc_u32 s15, s41, s10
	s_add_i32 s18, s3, s2
	s_cmp_lt_i32 s18, 0x800
	s_cselect_b64 s[10:11], -1, 0
	s_cmp_gt_i32 s18, 0x7ff
	s_cselect_b64 s[12:13], -1, 0
	s_and_b64 s[16:17], s[12:13], exec
	s_cselect_b32 s16, s2, s18
	s_ashr_i32 s35, s16, 8
	s_lshl_b32 s36, s16, 2
	v_readlane_b32 s37, v245, 7
	s_lshl_b32 s16, s35, 10
	s_and_b32 s27, s36, 0x3c0
	s_or_b32 s37, s27, s16
	s_mul_i32 s17, s35, 0x3480
	s_mul_hi_i32 s16, s35, 0x3480
	s_add_u32 s18, s40, s17
	s_addc_u32 s19, s41, s16
	s_lshl_b32 s29, s29, 2
	s_add_i32 s16, s29, 0x2040
	s_ashr_i32 s17, s16, 31
	s_lshl_b64 s[30:31], s[16:17], 10
	s_or_b32 s30, s30, s28
	v_mov_b32_e32 v5, s31
	v_or_b32_e32 v4, s30, v16
	v_lshl_add_u64 v[0:1], v[4:5], 3, s[8:9]
	v_and_or_b32 v29, s25, 60, v61
	global_load_dwordx4 v[38:41], v[0:1], off
	global_load_dwordx4 v[42:45], v[0:1], off offset:16
	v_or_b32_e32 v0, s34, v29
	v_ashrrev_i32_e32 v1, 31, v0
	v_readlane_b32 s42, v245, 12
	v_readlane_b32 s43, v245, 13
	v_readlane_b32 s44, v245, 14
	v_readlane_b32 s45, v245, 15
	v_readlane_b32 s46, v245, 16
	v_readlane_b32 s47, v245, 17
	v_readlane_b32 s48, v245, 18
	v_readlane_b32 s49, v245, 19
	v_readlane_b32 s50, v245, 20
	v_readlane_b32 s51, v245, 21
	v_lshlrev_b64 v[22:23], 8, v[0:1]
	v_or_b32_e32 v0, s28, v29
	v_or_b32_e32 v0, 0x800, v0
	s_mul_i32 s30, s16, 0x3480
	v_readlane_b32 s40, v245, 22
	v_lshlrev_b32_e32 v27, 2, v0
	s_mul_hi_i32 s31, s16, 0x3480
	s_add_u32 s30, s20, s30
	v_readlane_b32 s41, v245, 23
	s_addc_u32 s31, s21, s31
	s_nop 3
	global_load_dword v26, v27, s[40:41]
	global_load_dword v33, v27, s[14:15]
	global_load_dword v32, v27, s[30:31]
	s_lshl_b32 s30, s35, 2
	s_add_i32 s14, s30, 0x2040
	v_lshl_add_u64 v[0:1], v[18:19], 0, v[22:23]
	v_and_or_b32 v30, s36, 60, v61
	s_ashr_i32 s15, s14, 31
	global_load_dwordx4 v[46:49], v[0:1], off
	v_or_b32_e32 v0, s37, v30
	s_lshl_b64 s[34:35], s[14:15], 10
	v_ashrrev_i32_e32 v1, 31, v0
	v_or_b32_e32 v6, s27, v30
	v_lshl_add_u64 v[4:5], v[4:5], 2, s[6:7]
	s_or_b32 s31, s34, s27
	v_lshlrev_b64 v[24:25], 8, v[0:1]
	v_or_b32_e32 v6, 0x800, v6
	global_load_dwordx4 v[50:53], v[4:5], off
	v_mov_b32_e32 v5, s35
	v_or_b32_e32 v4, s31, v16
	s_mul_i32 s34, s14, 0x3480
	v_lshl_add_u64 v[0:1], v[18:19], 0, v[24:25]
	v_lshlrev_b32_e32 v28, 2, v6
	v_lshl_add_u64 v[6:7], v[4:5], 2, s[6:7]
	v_lshl_add_u64 v[12:13], v[4:5], 3, s[8:9]
	s_mul_hi_i32 s31, s14, 0x3480
	s_add_u32 s34, s20, s34
	global_load_dwordx4 v[0:3], v[0:1], off
	s_nop 0
	global_load_dwordx4 v[8:11], v[12:13], off offset:16
	s_nop 0
	global_load_dwordx4 v[4:7], v[6:7], off
	s_nop 0
	global_load_dwordx4 v[12:15], v[12:13], off
	s_addc_u32 s35, s21, s31
	global_load_dword v17, v28, s[40:41]
	global_load_dword v37, v28, s[18:19]
	global_load_dword v31, v28, s[34:35]
	s_add_i32 s64, s29, 0x2041
	s_ashr_i32 s65, s64, 31
	s_lshl_b64 s[66:67], s[64:65], 10
	v_mov_b32_e32 v236, s28
	v_or3_b32 v236, s66, v236, v16
	v_or3_b32 v237, s67, 0, 0
	s_mul_hi_i32 s67, s64, 0x3480
	s_mul_i32 s66, s64, 0x3480
	s_add_u32 s66, s20, s66
	s_addc_u32 s67, s21, s67
	v_lshl_add_u64 v[238:239], v[236:237], 3, s[8:9]
	global_load_dwordx4 v[148:151], v[238:239], off
	global_load_dwordx4 v[152:155], v[238:239], off offset:16
	global_load_dword v172, v27, s[66:67]
	v_lshl_add_u64 v[238:239], v[236:237], 2, s[6:7]
	global_load_dwordx4 v[156:159], v[238:239], off
	s_add_i32 s64, s30, 0x2041
	s_ashr_i32 s65, s64, 31
	s_lshl_b64 s[66:67], s[64:65], 10
	v_mov_b32_e32 v236, s27
	v_or3_b32 v236, s66, v236, v16
	v_or3_b32 v237, s67, 0, 0
	s_mul_hi_i32 s67, s64, 0x3480
	s_mul_i32 s66, s64, 0x3480
	s_add_u32 s66, s20, s66
	s_addc_u32 s67, s21, s67
	v_lshl_add_u64 v[238:239], v[236:237], 3, s[8:9]
	global_load_dwordx4 v[160:163], v[238:239], off
	global_load_dwordx4 v[164:167], v[238:239], off offset:16
	global_load_dword v173, v28, s[66:67]
	v_lshl_add_u64 v[238:239], v[236:237], 2, s[6:7]
	global_load_dwordx4 v[168:171], v[238:239], off
	s_add_i32 s64, s29, 0x2042
	s_ashr_i32 s65, s64, 31
	s_lshl_b64 s[66:67], s[64:65], 10
	v_mov_b32_e32 v236, s28
	v_or3_b32 v236, s66, v236, v16
	v_or3_b32 v237, s67, 0, 0
	s_mul_hi_i32 s67, s64, 0x3480
	s_mul_i32 s66, s64, 0x3480
	s_add_u32 s66, s20, s66
	s_addc_u32 s67, s21, s67
	v_lshl_add_u64 v[238:239], v[236:237], 3, s[8:9]
	global_load_dwordx4 v[180:183], v[238:239], off
	global_load_dwordx4 v[184:187], v[238:239], off offset:16
	global_load_dword v204, v27, s[66:67]
	v_lshl_add_u64 v[238:239], v[236:237], 2, s[6:7]
	global_load_dwordx4 v[188:191], v[238:239], off
	s_add_i32 s64, s30, 0x2042
	s_ashr_i32 s65, s64, 31
	s_lshl_b64 s[66:67], s[64:65], 10
	v_mov_b32_e32 v236, s27
	v_or3_b32 v236, s66, v236, v16
	v_or3_b32 v237, s67, 0, 0
	s_mul_hi_i32 s67, s64, 0x3480
	s_mul_i32 s66, s64, 0x3480
	s_add_u32 s66, s20, s66
	s_addc_u32 s67, s21, s67
	v_lshl_add_u64 v[238:239], v[236:237], 3, s[8:9]
	global_load_dwordx4 v[192:195], v[238:239], off
	global_load_dwordx4 v[196:199], v[238:239], off offset:16
	global_load_dword v205, v28, s[66:67]
	v_lshl_add_u64 v[238:239], v[236:237], 2, s[6:7]
	global_load_dwordx4 v[200:203], v[238:239], off
	s_add_i32 s64, s29, 0x2043
	s_ashr_i32 s65, s64, 31
	s_lshl_b64 s[66:67], s[64:65], 10
	v_mov_b32_e32 v236, s28
	v_or3_b32 v236, s66, v236, v16
	v_or3_b32 v237, s67, 0, 0
	s_mul_hi_i32 s67, s64, 0x3480
	s_mul_i32 s66, s64, 0x3480
	s_add_u32 s66, s20, s66
	s_addc_u32 s67, s21, s67
	v_lshl_add_u64 v[238:239], v[236:237], 3, s[8:9]
	global_load_dwordx4 v[210:213], v[238:239], off
	global_load_dwordx4 v[214:217], v[238:239], off offset:16
	global_load_dword v234, v27, s[66:67]
	v_lshl_add_u64 v[238:239], v[236:237], 2, s[6:7]
	global_load_dwordx4 v[218:221], v[238:239], off
	s_add_i32 s64, s30, 0x2043
	s_ashr_i32 s65, s64, 31
	s_lshl_b64 s[66:67], s[64:65], 10
	v_mov_b32_e32 v236, s27
	v_or3_b32 v236, s66, v236, v16
	v_or3_b32 v237, s67, 0, 0
	s_mul_hi_i32 s67, s64, 0x3480
	s_mul_i32 s66, s64, 0x3480
	s_add_u32 s66, s20, s66
	s_addc_u32 s67, s21, s67
	v_lshl_add_u64 v[238:239], v[236:237], 3, s[8:9]
	global_load_dwordx4 v[222:225], v[238:239], off
	global_load_dwordx4 v[226:229], v[238:239], off offset:16
	global_load_dword v235, v28, s[66:67]
	v_lshl_add_u64 v[238:239], v[236:237], 2, s[6:7]
	global_load_dwordx4 v[230:233], v[238:239], off
	v_lshlrev_b32_e32 v29, 2, v29
	v_readlane_b32 s38, v245, 8
	v_readlane_b32 s39, v245, 9
	v_readlane_b32 s42, v245, 24
	v_readlane_b32 s43, v245, 25
	v_readlane_b32 s44, v245, 26
	v_readlane_b32 s45, v245, 27
	v_readlane_b32 s46, v245, 28
	v_readlane_b32 s47, v245, 29
	v_readlane_b32 s48, v245, 30
	v_readlane_b32 s49, v245, 31
	v_readlane_b32 s50, v245, 32
	v_readlane_b32 s51, v245, 33
	v_readlane_b32 s52, v245, 34
	v_readlane_b32 s53, v245, 35
	v_readlane_b32 s54, v245, 36
	v_readlane_b32 s55, v245, 37
	s_waitcnt vmcnt(37)
	v_lshlrev_b32_e32 v55, 16, v40
	v_and_b32_e32 v35, 0xffff0000, v40
	v_lshlrev_b32_e32 v40, 16, v39
	v_lshlrev_b32_e32 v54, 16, v38
	s_waitcnt vmcnt(36)
	v_lshlrev_b32_e32 v56, 16, v42
	v_lshlrev_b32_e32 v57, 16, v44
	v_and_b32_e32 v34, 0xffff0000, v38
	v_and_b32_e32 v36, 0xffff0000, v42
	v_and_b32_e32 v38, 0xffff0000, v44
	v_lshlrev_b32_e32 v42, 16, v41
	v_lshlrev_b32_e32 v44, 16, v43
	v_lshlrev_b32_e32 v58, 16, v45
	v_and_b32_e32 v39, 0xffff0000, v39
	v_and_b32_e32 v41, 0xffff0000, v41
	v_and_b32_e32 v43, 0xffff0000, v43
	v_and_b32_e32 v45, 0xffff0000, v45
	s_waitcnt vmcnt(33)
	v_sub_f32_e32 v33, v33, v32
	v_fma_f32 v59, v26, v33, v32
	s_waitcnt vmcnt(32)
	v_mul_f32 v33, v46, v40
	v_mul_f32 v40, v48, v44
	v_mul_f32 v34, v59, v34
	v_mul_f32 v35, v59, v35
	s_nop 0
	v_fma_f32 v33, v47, v42, v33
	v_fma_f32 v40, v49, v58, v40
	s_nop 0
	v_add_f32 v33, v33, v40
	s_nop 1
	v_add_f32_dpp v33, v33, v33 row_ror:8 row_mask:0xf bank_mask:0xf bound_ctrl:1
	s_nop 1
	v_add_f32_dpp v33, v33, v33 row_ror:4 row_mask:0xf bank_mask:0xf bound_ctrl:1
	s_nop 1
	v_add_f32_dpp v33, v33, v33 row_ror:2 row_mask:0xf bank_mask:0xf bound_ctrl:1
	s_nop 1
	v_add_f32_dpp v40, v33, v33 row_ror:1 row_mask:0xf bank_mask:0xf bound_ctrl:1
	v_fma_f32 v33, v40, v39, v34
	v_fma_f32 v34, v40, v41, v35
	v_mul_f32 v35, v59, v36
	v_mul_f32 v36, v59, v38
	s_waitcnt vmcnt(31)
	v_fma_f32 v33, v46, v50, v33
	v_fma_f32 v35, v40, v43, v35
	v_fma_f32 v34, v47, v51, v34
	v_fma_f32 v36, v40, v45, v36
	s_nop 0
	v_mul_f32 v38, v33, v54
	v_fma_f32 v35, v48, v52, v35
	v_fma_f32 v36, v49, v53, v36
	s_nop 0
	v_fma_f32 v38, v34, v55, v38
	v_mul_f32 v39, v35, v56
	s_nop 0
	v_fma_f32 v39, v36, v57, v39
	s_nop 0
	v_add_f32 v38, v38, v39
	v_mov_b32_e32 v39, 0
	s_nop 0
	v_add_f32_dpp v38, v38, v38 row_ror:8 row_mask:0xf bank_mask:0xf bound_ctrl:1
	s_nop 1
	v_add_f32_dpp v38, v38, v38 row_ror:4 row_mask:0xf bank_mask:0xf bound_ctrl:1
	s_nop 1
	v_add_f32_dpp v38, v38, v38 row_ror:2 row_mask:0xf bank_mask:0xf bound_ctrl:1
	s_nop 1
	v_mov_b32_dpp v39, v38 row_ror:1 row_mask:0xf bank_mask:0xf
	s_and_saveexec_b64 s[18:19], s[4:5]
	s_cbranch_execz .LBB0_804
	s_lshl_b64 s[16:17], s[16:17], 12
	s_add_u32 s16, s22, s16
	s_addc_u32 s17, s23, s17
	s_lshl_b32 s31, s28, 2
	s_add_u32 s16, s16, s31
	s_addc_u32 s17, s17, 0
	v_add_f32_e32 v38, v38, v39
	global_store_dword v29, v38, s[16:17]
